# all-to-all release in the grid barriers: each XCD leader adds to all eight per-XCD release counters, everyone polls its own (no top counter, no leader poll, no XGEN hop)
# speedup vs baseline: 1.0279x; 1.0279x over previous
; __device__ __forceinline__ unsigned xb_ld(unsigned* p)              { return __hip_atomic_load(p, __ATOMIC_RELAXED, __HIP_MEMORY_SCOPE_AGENT); }
; __device__ __forceinline__ unsigned xb_add(unsigned* p, unsigned v) { return __hip_atomic_fetch_add(p, v, __ATOMIC_RELAXED, __HIP_MEMORY_SCOPE_AGENT); }
; #define XB_SPIN(cond, bar) do { unsigned _sp = 0; while (cond) { __builtin_amdgcn_s_sleep(1); \
;     if ((++_sp & 255u) == 0u) { if (xb_ld(&(bar)[XB_TMO])) break; if (_sp > XB_SPIN_CAP) { atomicAdd(&(bar)[XB_TMO], 1u); break; } } } } while (0)
; __device__ __forceinline__ void xcd_barrier(const XcdBarrier& b) {
;     ...
;     if (threadIdx.x == 0) {
;         unsigned* bar = b.bar;
;         __builtin_amdgcn_s_waitcnt(0);
;         unsigned nloc = b.st[0], nx = b.st[1];
;         if (nloc == 0u) { xcd_barrier_complete(bar, b.x, nloc, nx); b.st[0] = nloc; b.st[1] = nx; }
;         const unsigned old = xb_add(&bar[XB_XSUB(b.x)], 1u);
;         const unsigned gen = old / nloc;
;         if (old + 1u == (gen + 1u) * nloc) {
;             __builtin_amdgcn_fence(__ATOMIC_RELEASE, "agent");
;             asm volatile("s_waitcnt vmcnt(0)" ::: "memory");
;             const unsigned og = xb_add(&bar[XB_TOP], 1u);
;             const unsigned tg = og / nx;
;             if (og + 1u == (tg + 1u) * nx) xb_add(&bar[XB_TOPGEN], 1u);
;             else XB_SPIN(xb_ld(&bar[XB_TOPGEN]) == tg, bar);
;             __builtin_amdgcn_fence(__ATOMIC_ACQUIRE, "agent");
;             xb_add(&bar[XB_XGEN(b.x)], 1u);
;             asm volatile("s_waitcnt vmcnt(0)" ::: "memory");
.LBB0_151:
	s_waitcnt lgkmcnt(0)
	v_readfirstlane_b32 s14, v2
	v_readfirstlane_b32 s15, v0
	s_lshl_b32 s4, s3, 8
	s_add_u32 s6, s78, 0x1701400
	s_addc_u32 s7, s79, 0
	s_add_u32 s6, s6, s4
	s_addc_u32 s7, s7, 0
	s_add_u32 s10, s78, 0x1703c00
	s_addc_u32 s11, s79, 0
	s_lshr_b32 s4, s4, 1
	s_add_u32 s8, s10, s4
	s_addc_u32 s9, s11, 0
	v_mov_b32_e32 v0, 0
	v_mov_b32_e32 v1, 1
	global_atomic_add v2, v0, v1, s[6:7] sc0
	buffer_inv sc1
	s_waitcnt vmcnt(1)
	v_readfirstlane_b32 s4, v2
	s_nop 3
	s_add_i32 s4, s4, 1
	s_cmp_lg_u32 s4, s14
	s_cbranch_scc1 .Lxb_local_p
	global_atomic_add v0, v1, s[10:11] offset:0
	global_atomic_add v0, v1, s[10:11] offset:128
	global_atomic_add v0, v1, s[10:11] offset:256
	global_atomic_add v0, v1, s[10:11] offset:384
	global_atomic_add v0, v1, s[10:11] offset:512
	global_atomic_add v0, v1, s[10:11] offset:640
	global_atomic_add v0, v1, s[10:11] offset:768
	global_atomic_add v0, v1, s[10:11] offset:896

; __device__ __forceinline__ unsigned xb_ld(unsigned* p)              { return __hip_atomic_load(p, __ATOMIC_RELAXED, __HIP_MEMORY_SCOPE_AGENT); }
; __device__ __forceinline__ unsigned xb_add(unsigned* p, unsigned v) { return __hip_atomic_fetch_add(p, v, __ATOMIC_RELAXED, __HIP_MEMORY_SCOPE_AGENT); }
; #define XB_SPIN(cond, bar) do { unsigned _sp = 0; while (cond) { __builtin_amdgcn_s_sleep(1); \
;     if ((++_sp & 255u) == 0u) { if (xb_ld(&(bar)[XB_TMO])) break; if (_sp > XB_SPIN_CAP) { atomicAdd(&(bar)[XB_TMO], 1u); break; } } } } while (0)
; __device__ __forceinline__ void xcd_barrier(const XcdBarrier& b) {
;     ...
;             else XB_SPIN(xb_ld(&bar[XB_TOPGEN]) == tg, bar);
;             __builtin_amdgcn_fence(__ATOMIC_ACQUIRE, "agent");
;             xb_add(&bar[XB_XGEN(b.x)], 1u);
;             asm volatile("s_waitcnt vmcnt(0)" ::: "memory");
;         } else {
;             XB_SPIN(xb_ld(&bar[XB_XGEN(b.x)]) == gen, bar);
;             __builtin_amdgcn_fence(__ATOMIC_ACQUIRE, "agent");
;             asm volatile("s_waitcnt vmcnt(0)" ::: "memory");
;         }
.Lxb_gen_p:
	global_load_dword v2, v0, s[8:9] sc1
	s_waitcnt vmcnt(0)
	v_readfirstlane_b32 s5, v2
	s_nop 3
	s_cmp_ge_u32 s5, s15
	s_cbranch_scc1 .Lxb_gen_p_done
	s_sleep 1
	s_add_i32 s4, s4, 1
	s_cmp_lt_u32 s4, 0x40000
	s_cbranch_scc1 .Lxb_gen_p

; __device__ __forceinline__ unsigned xb_ld(unsigned* p)              { return __hip_atomic_load(p, __ATOMIC_RELAXED, __HIP_MEMORY_SCOPE_AGENT); }
; __device__ __forceinline__ unsigned xb_add(unsigned* p, unsigned v) { return __hip_atomic_fetch_add(p, v, __ATOMIC_RELAXED, __HIP_MEMORY_SCOPE_AGENT); }
; #define XB_SPIN(cond, bar) do { unsigned _sp = 0; while (cond) { __builtin_amdgcn_s_sleep(1); \
;     if ((++_sp & 255u) == 0u) { if (xb_ld(&(bar)[XB_TMO])) break; if (_sp > XB_SPIN_CAP) { atomicAdd(&(bar)[XB_TMO], 1u); break; } } } } while (0)
; __device__ __forceinline__ void xcd_barrier(const XcdBarrier& b) {
;     asm volatile("s_waitcnt vmcnt(0)" ::: "memory");
;     __syncthreads();
;     if (threadIdx.x == 0) {
;         unsigned* bar = b.bar;
;         __builtin_amdgcn_s_waitcnt(0);
;         unsigned nloc = b.st[0], nx = b.st[1];
;         if (nloc == 0u) { xcd_barrier_complete(bar, b.x, nloc, nx); b.st[0] = nloc; b.st[1] = nx; }
;         const unsigned old = xb_add(&bar[XB_XSUB(b.x)], 1u);
;         const unsigned gen = old / nloc;
;         if (old + 1u == (gen + 1u) * nloc) {
;             __builtin_amdgcn_fence(__ATOMIC_RELEASE, "agent");
;             asm volatile("s_waitcnt vmcnt(0)" ::: "memory");
;             const unsigned og = xb_add(&bar[XB_TOP], 1u);
;             const unsigned tg = og / nx;
;             if (og + 1u == (tg + 1u) * nx) xb_add(&bar[XB_TOPGEN], 1u);
;             else XB_SPIN(xb_ld(&bar[XB_TOPGEN]) == tg, bar);
;             __builtin_amdgcn_fence(__ATOMIC_ACQUIRE, "agent");
;             xb_add(&bar[XB_XGEN(b.x)], 1u);
;             asm volatile("s_waitcnt vmcnt(0)" ::: "memory");
.LBB0_207:
	s_getreg_b32 s2, hwreg(HW_REG_XCC_ID, 0, 4)
	s_waitcnt vmcnt(0)
	s_barrier
	s_mov_b64 s[0:1], exec
	v_readlane_b32 s4, v253, 2
	v_readlane_b32 s5, v253, 3
	s_and_b64 s[4:5], s[0:1], s[4:5]
	s_mov_b64 exec, s[4:5]
	s_cbranch_execz .LBB0_259
	v_mov_b32_e32 v0, 0x20020
	s_waitcnt vmcnt(0) lgkmcnt(0)
	ds_read2_b32 v[2:3], v0 offset1:1
	s_and_b32 s3, s2, 15
	s_lshl_b32 s3, s3, 8
	s_add_u32 s6, s78, 0x1701400
	s_addc_u32 s7, s79, 0
	s_add_u32 s6, s6, s3
	s_addc_u32 s7, s7, 0
	s_add_u32 s10, s78, 0x1703c00
	s_addc_u32 s11, s79, 0
	s_lshr_b32 s3, s3, 1
	s_add_u32 s8, s10, s3
	s_addc_u32 s9, s11, 0
	s_waitcnt lgkmcnt(0)
	v_readfirstlane_b32 s30, v2
	v_readfirstlane_b32 s31, v3
	s_nop 3
	s_cmp_eq_u32 s30, 0
	s_cbranch_scc1 .Lxb_slow_n
	s_lshl_b32 s29, s66, 2
	s_add_i32 s29, s29, 1
	global_atomic_add v2, v173, v212, s[6:7] sc0
	buffer_inv sc1
	s_add_i32 s32, s29, 1
	s_mul_i32 s5, s32, s30
	s_mul_i32 s32, s32, s31
	s_waitcnt vmcnt(1)
	v_readfirstlane_b32 s3, v2
	s_nop 3
	s_add_i32 s3, s3, 1
	s_cmp_lg_u32 s3, s5
	s_cbranch_scc1 .Lxb_local_n
	global_atomic_add v173, v212, s[10:11] offset:0
	global_atomic_add v173, v212, s[10:11] offset:128
	global_atomic_add v173, v212, s[10:11] offset:256
	global_atomic_add v173, v212, s[10:11] offset:384
	global_atomic_add v173, v212, s[10:11] offset:512
	global_atomic_add v173, v212, s[10:11] offset:640
	global_atomic_add v173, v212, s[10:11] offset:768
	global_atomic_add v173, v212, s[10:11] offset:896

; __device__ __forceinline__ unsigned xb_ld(unsigned* p)              { return __hip_atomic_load(p, __ATOMIC_RELAXED, __HIP_MEMORY_SCOPE_AGENT); }
; #define XB_SPIN(cond, bar) do { unsigned _sp = 0; while (cond) { __builtin_amdgcn_s_sleep(1); \
;     if ((++_sp & 255u) == 0u) { if (xb_ld(&(bar)[XB_TMO])) break; if (_sp > XB_SPIN_CAP) { atomicAdd(&(bar)[XB_TMO], 1u); break; } } } } while (0)
; __device__ __forceinline__ void xcd_barrier(const XcdBarrier& b) {
;     ...
;         } else {
;             XB_SPIN(xb_ld(&bar[XB_XGEN(b.x)]) == gen, bar);
;             __builtin_amdgcn_fence(__ATOMIC_ACQUIRE, "agent");
;             asm volatile("s_waitcnt vmcnt(0)" ::: "memory");
;         }
.Lxb_gen_n:
	global_load_dword v2, v173, s[8:9] sc1
	s_waitcnt vmcnt(0)
	v_readfirstlane_b32 s5, v2
	s_nop 3
	s_cmp_ge_u32 s5, s32
	s_cbranch_scc1 .Lxb_gen_n_done
	s_sleep 1
	s_add_i32 s3, s3, 1
	s_cmp_lt_u32 s3, 0x40000
	s_cbranch_scc1 .Lxb_gen_n

; __device__ __forceinline__ unsigned xb_ld(unsigned* p)              { return __hip_atomic_load(p, __ATOMIC_RELAXED, __HIP_MEMORY_SCOPE_AGENT); }
; __device__ __forceinline__ unsigned xb_add(unsigned* p, unsigned v) { return __hip_atomic_fetch_add(p, v, __ATOMIC_RELAXED, __HIP_MEMORY_SCOPE_AGENT); }
; #define XB_SPIN(cond, bar) do { unsigned _sp = 0; while (cond) { __builtin_amdgcn_s_sleep(1); \
;     if ((++_sp & 255u) == 0u) { if (xb_ld(&(bar)[XB_TMO])) break; if (_sp > XB_SPIN_CAP) { atomicAdd(&(bar)[XB_TMO], 1u); break; } } } } while (0)
; __device__ __forceinline__ void xcd_barrier(const XcdBarrier& b) {
;     asm volatile("s_waitcnt vmcnt(0)" ::: "memory");
;     __syncthreads();
;     if (threadIdx.x == 0) {
;         unsigned* bar = b.bar;
;         __builtin_amdgcn_s_waitcnt(0);
;         unsigned nloc = b.st[0], nx = b.st[1];
;         if (nloc == 0u) { xcd_barrier_complete(bar, b.x, nloc, nx); b.st[0] = nloc; b.st[1] = nx; }
;         const unsigned old = xb_add(&bar[XB_XSUB(b.x)], 1u);
;         const unsigned gen = old / nloc;
;         if (old + 1u == (gen + 1u) * nloc) {
;             __builtin_amdgcn_fence(__ATOMIC_RELEASE, "agent");
;             asm volatile("s_waitcnt vmcnt(0)" ::: "memory");
;             const unsigned og = xb_add(&bar[XB_TOP], 1u);
;             const unsigned tg = og / nx;
;             if (og + 1u == (tg + 1u) * nx) xb_add(&bar[XB_TOPGEN], 1u);
;             else XB_SPIN(xb_ld(&bar[XB_TOPGEN]) == tg, bar);
;             __builtin_amdgcn_fence(__ATOMIC_ACQUIRE, "agent");
;             xb_add(&bar[XB_XGEN(b.x)], 1u);
;             asm volatile("s_waitcnt vmcnt(0)" ::: "memory");
.LBB0_386:
	s_getreg_b32 s2, hwreg(HW_REG_XCC_ID, 0, 4)
	s_waitcnt vmcnt(0)
	v_writelane_b32 v255, s0, 13
	s_waitcnt vmcnt(0)
	s_barrier
	v_writelane_b32 v255, s1, 14
	s_mov_b64 s[0:1], exec
	v_readlane_b32 s4, v253, 2
	v_readlane_b32 s5, v253, 3
	s_and_b64 s[4:5], s[0:1], s[4:5]
	s_mov_b64 exec, s[4:5]
	s_cbranch_execz .LBB0_439
	v_mov_b32_e32 v0, 0x20020
	s_waitcnt vmcnt(0) lgkmcnt(0)
	ds_read2_b32 v[2:3], v0 offset1:1
	s_and_b32 s3, s2, 15
	s_lshl_b32 s3, s3, 8
	s_add_u32 s6, s78, 0x1701400
	s_addc_u32 s7, s79, 0
	s_add_u32 s6, s6, s3
	s_addc_u32 s7, s7, 0
	s_add_u32 s10, s78, 0x1703c00
	s_addc_u32 s11, s79, 0
	s_lshr_b32 s3, s3, 1
	s_add_u32 s8, s10, s3
	s_addc_u32 s9, s11, 0
	s_waitcnt lgkmcnt(0)
	v_readfirstlane_b32 s30, v2
	v_readfirstlane_b32 s31, v3
	s_nop 3
	s_cmp_eq_u32 s30, 0
	s_cbranch_scc1 .Lxb_slow_i
	s_lshl_b32 s29, s66, 2
	s_add_i32 s29, s29, 2
	global_atomic_add v2, v173, v212, s[6:7] sc0
	buffer_inv sc1
	s_add_i32 s32, s29, 1
	s_mul_i32 s5, s32, s30
	s_mul_i32 s32, s32, s31
	s_waitcnt vmcnt(1)
	v_readfirstlane_b32 s3, v2
	s_nop 3
	s_add_i32 s3, s3, 1
	s_cmp_lg_u32 s3, s5
	s_cbranch_scc1 .Lxb_local_i
	buffer_wbl2 sc1
	s_waitcnt vmcnt(0)
	global_atomic_add v173, v212, s[10:11] offset:0
	global_atomic_add v173, v212, s[10:11] offset:128
	global_atomic_add v173, v212, s[10:11] offset:256
	global_atomic_add v173, v212, s[10:11] offset:384
	global_atomic_add v173, v212, s[10:11] offset:512
	global_atomic_add v173, v212, s[10:11] offset:640
	global_atomic_add v173, v212, s[10:11] offset:768
	global_atomic_add v173, v212, s[10:11] offset:896

; __device__ __forceinline__ unsigned xb_ld(unsigned* p)              { return __hip_atomic_load(p, __ATOMIC_RELAXED, __HIP_MEMORY_SCOPE_AGENT); }
; __device__ __forceinline__ unsigned xb_add(unsigned* p, unsigned v) { return __hip_atomic_fetch_add(p, v, __ATOMIC_RELAXED, __HIP_MEMORY_SCOPE_AGENT); }
; #define XB_SPIN(cond, bar) do { unsigned _sp = 0; while (cond) { __builtin_amdgcn_s_sleep(1); \
;     if ((++_sp & 255u) == 0u) { if (xb_ld(&(bar)[XB_TMO])) break; if (_sp > XB_SPIN_CAP) { atomicAdd(&(bar)[XB_TMO], 1u); break; } } } } while (0)
; __device__ __forceinline__ void xcd_barrier(const XcdBarrier& b) {
;     asm volatile("s_waitcnt vmcnt(0)" ::: "memory");
;     __syncthreads();
;     if (threadIdx.x == 0) {
;         unsigned* bar = b.bar;
;         __builtin_amdgcn_s_waitcnt(0);
;         unsigned nloc = b.st[0], nx = b.st[1];
;         if (nloc == 0u) { xcd_barrier_complete(bar, b.x, nloc, nx); b.st[0] = nloc; b.st[1] = nx; }
;         const unsigned old = xb_add(&bar[XB_XSUB(b.x)], 1u);
;         const unsigned gen = old / nloc;
;         if (old + 1u == (gen + 1u) * nloc) {
;             __builtin_amdgcn_fence(__ATOMIC_RELEASE, "agent");
;             asm volatile("s_waitcnt vmcnt(0)" ::: "memory");
;             const unsigned og = xb_add(&bar[XB_TOP], 1u);
;             const unsigned tg = og / nx;
;             if (og + 1u == (tg + 1u) * nx) xb_add(&bar[XB_TOPGEN], 1u);
;             else XB_SPIN(xb_ld(&bar[XB_TOPGEN]) == tg, bar);
;             __builtin_amdgcn_fence(__ATOMIC_ACQUIRE, "agent");
;             xb_add(&bar[XB_XGEN(b.x)], 1u);
;             asm volatile("s_waitcnt vmcnt(0)" ::: "memory");
.LBB0_534:
	s_and_b64 vcc, exec, s[0:1]
	s_mov_b32 s93, s4
	s_cbranch_vccz .LBB0_441
	s_getreg_b32 s2, hwreg(HW_REG_XCC_ID, 0, 4)
	s_waitcnt vmcnt(0)
	s_barrier
	s_mov_b64 s[0:1], exec
	v_readlane_b32 s4, v253, 2
	v_readlane_b32 s5, v253, 3
	v_readlane_b32 s72, v254, 48
	v_readlane_b32 s80, v254, 50
	v_readlane_b32 s82, v254, 52
	v_readlane_b32 s92, v254, 54
	v_readlane_b32 s94, v254, 56
	v_readlane_b32 s98, v254, 58
	v_readlane_b32 s54, v254, 60
	v_readlane_b32 s56, v254, 62
	v_readlane_b32 s60, v255, 0
	v_readlane_b32 s62, v255, 2
	v_readlane_b32 s22, v255, 21
	s_and_b64 s[4:5], s[0:1], s[4:5]
	v_readlane_b32 s73, v254, 49
	v_readlane_b32 s81, v254, 51
	v_readlane_b32 s83, v254, 53
	v_readlane_b32 s93, v254, 55
	v_readlane_b32 s95, v254, 57
	v_readlane_b32 s99, v254, 59
	v_readlane_b32 s55, v254, 61
	v_readlane_b32 s57, v254, 63
	v_readlane_b32 s61, v255, 1
	v_readlane_b32 s63, v255, 3
	v_readlane_b32 s33, v255, 4
	v_readlane_b32 s85, v255, 5
	v_readlane_b32 s25, v254, 41
	v_readlane_b32 s28, v254, 43
	v_readlane_b32 s23, v255, 22
	s_mov_b64 exec, s[4:5]
	s_cbranch_execz .LBB0_587
	v_mov_b32_e32 v0, 0x20020
	s_waitcnt vmcnt(0) lgkmcnt(0)
	ds_read2_b32 v[2:3], v0 offset1:1
	s_and_b32 s3, s2, 15
	s_lshl_b32 s3, s3, 8
	s_add_u32 s6, s78, 0x1701400
	s_addc_u32 s7, s79, 0
	s_add_u32 s6, s6, s3
	s_addc_u32 s7, s7, 0
	s_add_u32 s10, s78, 0x1703c00
	s_addc_u32 s11, s79, 0
	s_lshr_b32 s3, s3, 1
	s_add_u32 s8, s10, s3
	s_addc_u32 s9, s11, 0
	s_waitcnt lgkmcnt(0)
	v_readfirstlane_b32 s30, v2
	v_readfirstlane_b32 s31, v3
	s_nop 3
	s_cmp_eq_u32 s30, 0
	s_cbranch_scc1 .Lxb_slow_m
	v_readlane_b32 s29, v255, 21
	s_nop 3
	s_lshl_b32 s29, s29, 2
	s_add_i32 s29, s29, 3
	global_atomic_add v2, v173, v212, s[6:7] sc0
	buffer_inv sc1
	s_add_i32 s32, s29, 1
	s_mul_i32 s5, s32, s30
	s_mul_i32 s32, s32, s31
	s_waitcnt vmcnt(1)
	v_readfirstlane_b32 s3, v2
	s_nop 3
	s_add_i32 s3, s3, 1
	s_cmp_lg_u32 s3, s5
	s_cbranch_scc1 .Lxb_local_m
	buffer_wbl2 sc1
	s_waitcnt vmcnt(0)
	global_atomic_add v173, v212, s[10:11] offset:0
	global_atomic_add v173, v212, s[10:11] offset:128
	global_atomic_add v173, v212, s[10:11] offset:256
	global_atomic_add v173, v212, s[10:11] offset:384
	global_atomic_add v173, v212, s[10:11] offset:512
	global_atomic_add v173, v212, s[10:11] offset:640
	global_atomic_add v173, v212, s[10:11] offset:768
	global_atomic_add v173, v212, s[10:11] offset:896

; __device__ __forceinline__ unsigned xb_ld(unsigned* p)              { return __hip_atomic_load(p, __ATOMIC_RELAXED, __HIP_MEMORY_SCOPE_AGENT); }
; __device__ __forceinline__ unsigned xb_add(unsigned* p, unsigned v) { return __hip_atomic_fetch_add(p, v, __ATOMIC_RELAXED, __HIP_MEMORY_SCOPE_AGENT); }
; #define XB_SPIN(cond, bar) do { unsigned _sp = 0; while (cond) { __builtin_amdgcn_s_sleep(1); \
;     if ((++_sp & 255u) == 0u) { if (xb_ld(&(bar)[XB_TMO])) break; if (_sp > XB_SPIN_CAP) { atomicAdd(&(bar)[XB_TMO], 1u); break; } } } } while (0)
; __device__ __forceinline__ void xcd_barrier(const XcdBarrier& b) {
;     asm volatile("s_waitcnt vmcnt(0)" ::: "memory");
;     __syncthreads();
;     if (threadIdx.x == 0) {
;         unsigned* bar = b.bar;
;         __builtin_amdgcn_s_waitcnt(0);
;         unsigned nloc = b.st[0], nx = b.st[1];
;         if (nloc == 0u) { xcd_barrier_complete(bar, b.x, nloc, nx); b.st[0] = nloc; b.st[1] = nx; }
;         const unsigned old = xb_add(&bar[XB_XSUB(b.x)], 1u);
;         const unsigned gen = old / nloc;
;         if (old + 1u == (gen + 1u) * nloc) {
;             __builtin_amdgcn_fence(__ATOMIC_RELEASE, "agent");
;             asm volatile("s_waitcnt vmcnt(0)" ::: "memory");
;             const unsigned og = xb_add(&bar[XB_TOP], 1u);
;             const unsigned tg = og / nx;
;             if (og + 1u == (tg + 1u) * nx) xb_add(&bar[XB_TOPGEN], 1u);
;             else XB_SPIN(xb_ld(&bar[XB_TOPGEN]) == tg, bar);
;             __builtin_amdgcn_fence(__ATOMIC_ACQUIRE, "agent");
;             xb_add(&bar[XB_XGEN(b.x)], 1u);
;             asm volatile("s_waitcnt vmcnt(0)" ::: "memory");
; __global__ void __launch_bounds__(512, 2) fwd_megakernel(Args a) {
;     ...
;             for (int step = 0; step < 2; ++step) {
;                 if ((step == 0) == small_first) { FRESH_TID();
;                     for (int t = bid; t < 256; t += G) g2_sample_tile((const bf16_t*)(a.ws + WS_H), (const bf16_t*)(a.ws + WS_WOUT) + (size_t)l * D * D, nullptr, XBase + (size_t)MP * D, a.out + (size_t)MP * D, l == 0 ? XB + (size_t)MP * D : nullptr, gate, lds, t, tid, lane, wave);
;                 } else {
;                     pg8::gemm_phase<pg8::EpiGate, pg8::StaticOrder, true, true>(lds, g, S, E);
;                 }
;             }
;         }
;         if (l == 0) GRID_BARRIER();
.LBB0_683:
	v_readlane_b32 s2, v255, 11
	v_readlane_b32 s3, v255, 12
	s_mov_b64 s[0:1], -1
	s_and_b64 vcc, exec, s[2:3]
	v_readlane_b32 s12, v255, 6
	s_mov_b64 s[26:27], 0x1000
	v_readlane_b32 s13, v255, 7
	s_cbranch_vccz .LBB0_190
	s_getreg_b32 s2, hwreg(HW_REG_XCC_ID, 0, 4)
	s_waitcnt vmcnt(0)
	s_barrier
	s_mov_b64 s[0:1], exec
	v_readlane_b32 s4, v253, 2
	v_readlane_b32 s5, v253, 3
	s_and_b64 s[4:5], s[0:1], s[4:5]
	s_mov_b64 exec, s[4:5]
	s_cbranch_execz .LBB0_189
	v_mov_b32_e32 v0, 0x20020
	s_waitcnt vmcnt(0) lgkmcnt(0)
	ds_read2_b32 v[2:3], v0 offset1:1
	s_and_b32 s3, s2, 15
	s_lshl_b32 s3, s3, 8
	s_add_u32 s6, s78, 0x1701400
	s_addc_u32 s7, s79, 0
	s_add_u32 s6, s6, s3
	s_addc_u32 s7, s7, 0
	s_add_u32 s10, s78, 0x1703c00
	s_addc_u32 s11, s79, 0
	s_lshr_b32 s3, s3, 1
	s_add_u32 s8, s10, s3
	s_addc_u32 s9, s11, 0
	s_waitcnt lgkmcnt(0)
	v_readfirstlane_b32 s30, v2
	v_readfirstlane_b32 s31, v3
	s_nop 3
	s_cmp_eq_u32 s30, 0
	s_cbranch_scc1 .Lxb_slow_o
	s_mov_b32 s29, 4
	global_atomic_add v2, v173, v212, s[6:7] sc0
	buffer_inv sc1
	s_add_i32 s32, s29, 1
	s_mul_i32 s5, s32, s30
	s_mul_i32 s32, s32, s31
	s_waitcnt vmcnt(1)
	v_readfirstlane_b32 s3, v2
	s_nop 3
	s_add_i32 s3, s3, 1
	s_cmp_lg_u32 s3, s5
	s_cbranch_scc1 .Lxb_local_o
	global_atomic_add v173, v212, s[10:11] offset:0
	global_atomic_add v173, v212, s[10:11] offset:128
	global_atomic_add v173, v212, s[10:11] offset:256
	global_atomic_add v173, v212, s[10:11] offset:384
	global_atomic_add v173, v212, s[10:11] offset:512
	global_atomic_add v173, v212, s[10:11] offset:640
	global_atomic_add v173, v212, s[10:11] offset:768
	global_atomic_add v173, v212, s[10:11] offset:896
